# attention: K3/V1 tile requests moved to unit start, step-0 vmcnt ladder re-derived so prefetched units do not drain V0 in step 0
# baseline (speedup 1.0000x reference)
.Latt_skip4:
	v_add3_u32 v214, 0, v0, v4
	s_add_i32 m0, s78, 0x9000
	s_nop 0
	global_load_lds_dwordx4 v216, s[38:39]
	s_add_i32 m0, s85, 0x9000
	s_nop 0
	global_load_lds_dwordx4 v216, s[40:41]
	s_add_i32 m0, s78, 0xe000
	s_nop 0
	global_load_lds_dwordx4 v216, s[42:43]
	s_waitcnt vmcnt(8) lgkmcnt(0)
	s_barrier
	ds_read_b128 v[2:5], v214
	ds_read_b128 v[6:9], v214 offset:512
	s_cmp_lg_u32 s1, 0
	s_cselect_b64 s[4:5], -1, 0
	v_lshlrev_b32_e32 v212, 2, v206
	v_or_b32_e32 v213, s74, v205
	s_and_b64 vcc, exec, s[4:5]
	s_waitcnt lgkmcnt(1)
	v_mfma_f32_32x32x16_bf16 v[48:63], v[2:5], v[176:179], v[32:47]
	s_waitcnt lgkmcnt(0)
	v_mfma_f32_32x32x16_bf16 v[32:47], v[6:9], v[176:179], v[32:47]
	ds_read_b128 v[2:5], v214 offset:2048
	ds_read_b128 v[6:9], v214 offset:2560
	s_waitcnt lgkmcnt(1)
	v_mfma_f32_32x32x16_bf16 v[48:63], v[2:5], v[168:171], v[48:63]
	s_waitcnt lgkmcnt(0)
	v_mfma_f32_32x32x16_bf16 v[32:47], v[6:9], v[168:171], v[32:47]
	ds_read_b128 v[2:5], v214 offset:4096
	ds_read_b128 v[6:9], v214 offset:4608
	s_waitcnt lgkmcnt(1)
	v_mfma_f32_32x32x16_bf16 v[48:63], v[2:5], v[164:167], v[48:63]
	s_waitcnt lgkmcnt(0)
	v_mfma_f32_32x32x16_bf16 v[32:47], v[6:9], v[164:167], v[32:47]
	ds_read_b128 v[2:5], v214 offset:6144
	ds_read_b128 v[6:9], v214 offset:6656
	s_waitcnt vmcnt(7) lgkmcnt(1)
	v_mfma_f32_32x32x16_bf16 v[48:63], v[2:5], v[156:159], v[48:63]
	s_waitcnt lgkmcnt(0)
	v_mfma_f32_32x32x16_bf16 v[32:47], v[6:9], v[156:159], v[32:47]
	ds_read_b128 v[2:5], v214 offset:8192
	ds_read_b128 v[6:9], v214 offset:8704
	s_waitcnt vmcnt(6) lgkmcnt(1)
	v_mfma_f32_32x32x16_bf16 v[48:63], v[2:5], v[148:151], v[48:63]
	s_waitcnt lgkmcnt(0)
	v_mfma_f32_32x32x16_bf16 v[32:47], v[6:9], v[148:151], v[32:47]
	ds_read_b128 v[2:5], v214 offset:10240
	ds_read_b128 v[6:9], v214 offset:10752
	s_waitcnt vmcnt(5) lgkmcnt(1)
	v_mfma_f32_32x32x16_bf16 v[48:63], v[2:5], v[144:147], v[48:63]
	s_waitcnt lgkmcnt(0)
	v_mfma_f32_32x32x16_bf16 v[32:47], v[6:9], v[144:147], v[32:47]
	s_nop 15
	s_nop 7
	s_cbranch_vccnz .LBB0_830
	v_subrev_u32_e32 v0, s13, v212
	v_add_u32_e32 v2, 32, v0
	v_cmp_le_i32_e32 vcc, v2, v213
	v_add_u32_e32 v2, 33, v0
	s_nop 6
	v_cndmask_b32_e32 v32, v203, v32, vcc
	v_cmp_lt_i32_e32 vcc, v0, v213
	s_nop 1
	v_cndmask_b32_e32 v49, v203, v49, vcc
	v_cmp_le_i32_e32 vcc, v0, v213
	s_nop 1
	v_cndmask_b32_e32 v48, v203, v48, vcc
	v_cmp_le_i32_e32 vcc, v2, v213
	v_or_b32_e32 v2, 2, v212
	s_nop 0
	v_cndmask_b32_e32 v33, v203, v33, vcc
	v_cmp_le_i32_e32 vcc, v2, v213
	v_add_u32_e32 v2, 34, v0
	s_nop 0
	v_cndmask_b32_e32 v50, v203, v50, vcc
	v_cmp_le_i32_e32 vcc, v2, v213
	v_or_b32_e32 v2, 3, v212
	s_nop 0
	v_cndmask_b32_e32 v34, v203, v34, vcc
	v_cmp_le_i32_e32 vcc, v2, v213
	v_add_u32_e32 v2, 35, v0
	s_nop 0
	v_cndmask_b32_e32 v51, v203, v51, vcc
	v_cmp_le_i32_e32 vcc, v2, v213
	v_add_u32_e32 v2, 8, v0
	s_nop 0
	v_cndmask_b32_e32 v35, v203, v35, vcc
	v_cmp_le_i32_e32 vcc, v2, v213
	v_add_u32_e32 v2, 40, v0
	s_nop 0
	v_cndmask_b32_e32 v52, v203, v52, vcc
	v_cmp_le_i32_e32 vcc, v2, v213
	v_add_u32_e32 v2, 9, v0
	s_nop 0
	v_cndmask_b32_e32 v36, v203, v36, vcc
	v_cmp_le_i32_e32 vcc, v2, v213
	v_add_u32_e32 v2, 41, v0
	s_nop 0
	v_cndmask_b32_e32 v53, v203, v53, vcc
	v_cmp_le_i32_e32 vcc, v2, v213
	v_add_u32_e32 v2, 10, v0
	s_nop 0
	v_cndmask_b32_e32 v37, v203, v37, vcc
	v_cmp_le_i32_e32 vcc, v2, v213
	v_add_u32_e32 v2, 42, v0
	s_nop 0
	v_cndmask_b32_e32 v54, v203, v54, vcc
	v_cmp_le_i32_e32 vcc, v2, v213
	v_add_u32_e32 v2, 11, v0
	s_nop 0
	v_cndmask_b32_e32 v38, v203, v38, vcc
	v_cmp_le_i32_e32 vcc, v2, v213
	v_add_u32_e32 v2, 43, v0
	s_nop 0
	v_cndmask_b32_e32 v55, v203, v55, vcc
	v_cmp_le_i32_e32 vcc, v2, v213
	v_add_u32_e32 v2, 16, v0
	s_nop 0
	v_cndmask_b32_e32 v39, v203, v39, vcc
	v_cmp_le_i32_e32 vcc, v2, v213
	v_add_u32_e32 v2, 48, v0
	s_nop 0
	v_cndmask_b32_e32 v56, v203, v56, vcc
	v_cmp_le_i32_e32 vcc, v2, v213
	v_add_u32_e32 v2, 17, v0
	s_nop 0
	v_cndmask_b32_e32 v40, v203, v40, vcc
	v_cmp_le_i32_e32 vcc, v2, v213
	v_add_u32_e32 v2, 49, v0
	s_nop 0
	v_cndmask_b32_e32 v57, v203, v57, vcc
	v_cmp_le_i32_e32 vcc, v2, v213
	v_add_u32_e32 v2, 18, v0
	s_nop 0
	v_cndmask_b32_e32 v41, v203, v41, vcc
	v_cmp_le_i32_e32 vcc, v2, v213
	v_add_u32_e32 v2, 50, v0
	s_nop 0
	v_cndmask_b32_e32 v58, v203, v58, vcc
	v_cmp_le_i32_e32 vcc, v2, v213
	v_add_u32_e32 v2, 19, v0
	s_nop 0
	v_cndmask_b32_e32 v42, v203, v42, vcc
	v_cmp_le_i32_e32 vcc, v2, v213
	v_add_u32_e32 v2, 51, v0
	s_nop 0
	v_cndmask_b32_e32 v59, v203, v59, vcc
	v_cmp_le_i32_e32 vcc, v2, v213
	v_add_u32_e32 v2, 24, v0
	s_nop 0
	v_cndmask_b32_e32 v43, v203, v43, vcc
	v_cmp_le_i32_e32 vcc, v2, v213
	v_add_u32_e32 v2, 56, v0
	s_nop 0
	v_cndmask_b32_e32 v60, v203, v60, vcc
	v_cmp_le_i32_e32 vcc, v2, v213
	v_add_u32_e32 v2, 25, v0
	s_nop 0
	v_cndmask_b32_e32 v44, v203, v44, vcc
	v_cmp_le_i32_e32 vcc, v2, v213
	v_add_u32_e32 v2, 57, v0
	s_nop 0
	v_cndmask_b32_e32 v61, v203, v61, vcc
	v_cmp_le_i32_e32 vcc, v2, v213
	v_add_u32_e32 v2, 26, v0
	s_nop 0
	v_cndmask_b32_e32 v45, v203, v45, vcc
	v_cmp_le_i32_e32 vcc, v2, v213
	v_add_u32_e32 v2, 58, v0
	s_nop 0
	v_cndmask_b32_e32 v62, v203, v62, vcc
	v_cmp_le_i32_e32 vcc, v2, v213
	v_add_u32_e32 v2, 27, v0
	v_add_u32_e32 v0, 59, v0
	v_cndmask_b32_e32 v46, v203, v46, vcc
	v_cmp_le_i32_e32 vcc, v2, v213
	s_nop 1
	v_cndmask_b32_e32 v63, v203, v63, vcc
	v_cmp_le_i32_e32 vcc, v0, v213
	s_nop 1
	v_cndmask_b32_e32 v47, v203, v47, vcc
.LBB0_830:
	v_lshlrev_b32_e32 v0, 1, v204
	v_lshrrev_b32_e32 v2, 2, v204
	v_and_b32_e32 v209, 32, v0
	v_lshlrev_b32_e32 v211, 3, v204
	v_and_or_b32 v2, v2, 3, v212
	v_add_u32_e32 v0, 0, v209
	v_and_b32_e32 v210, 24, v211
	v_lshlrev_b32_e32 v208, 6, v2
	v_add3_u32 v217, v0, v210, v208
	v_max3_f32 v0, v48, v49, v32
	v_max3_f32 v2, v50, v51, v33
	s_add_i32 s6, s83, s93
	v_max3_f32 v0, v0, v34, v35
	v_max3_f32 v2, v2, v54, v55
	s_add_i32 s1, s13, 0x100
	v_max3_f32 v0, v0, v52, v53
	v_max3_f32 v2, v2, v38, v39
	s_lshr_b32 s1, s1, 6
	v_max3_f32 v0, v0, v36, v37
	v_max3_f32 v2, v2, v58, v59
	v_lshl_add_u32 v207, v212, 2, s87
	v_max3_f32 v0, v0, v56, v57
	v_max3_f32 v2, v2, v42, v43
	s_mov_b32 s10, 1
	v_max3_f32 v0, v0, v40, v41
	v_max3_f32 v2, v2, v62, v63
	s_mov_b32 s23, 0
	v_max3_f32 v0, v0, v60, v61
	v_max3_f32 v2, v2, v46, v47
	s_andn2_b64 vcc, exec, s[4:5]
	v_max3_f32 v0, v0, v44, v45
	v_cmp_gt_u32_e64 s[4:5], 32, v204
	v_max_f32_e32 v0, v0, v2
	s_nop 0
	v_mov_b32_e32 v2, v0
	s_nop 1
	v_permlane32_swap_b32_e32 v0, v2
	v_max_f32_e32 v0, v0, v2
	s_nop 0
	v_add_f32_e32 v215, v1, v0
	v_sub_f32_e32 v2, v48, v0
	v_sub_f32_e32 v3, v32, v0
	v_sub_f32_e32 v4, v49, v0
	v_sub_f32_e32 v5, v33, v0
	v_sub_f32_e32 v6, v50, v0
	s_nop 0
	v_xor_b32_e32 v64, 0x80000000, v215
	v_mov_b32_e32 v65, v64
	v_mov_b32_e32 v66, v64
	v_mov_b32_e32 v67, v64
	v_mov_b32_e32 v68, v64
	v_mov_b32_e32 v69, v64
	v_mov_b32_e32 v70, v64
	v_mov_b32_e32 v71, v64
	v_mov_b32_e32 v72, v64
	v_mov_b32_e32 v73, v64
	v_mov_b32_e32 v74, v64
	v_mov_b32_e32 v75, v64
	v_mov_b32_e32 v76, v64
	v_mov_b32_e32 v77, v64
	v_mov_b32_e32 v78, v64
	v_mov_b32_e32 v79, v64
	s_waitcnt vmcnt(3) lgkmcnt(0)
	s_barrier
	ds_read_b128 v[196:199], v214 offset:12288
	ds_read_b128 v[184:187], v214 offset:12800
	ds_read_b128 v[188:191], v214 offset:14336
	ds_read_b128 v[192:195], v214 offset:14848
	v_sub_f32_e32 v7, v34, v0
	v_sub_f32_e32 v8, v51, v0
	v_sub_f32_e32 v9, v35, v0
	v_sub_f32_e32 v10, v52, v0
	v_sub_f32_e32 v11, v36, v0
	v_sub_f32_e32 v12, v53, v0
	v_sub_f32_e32 v13, v37, v0
	v_sub_f32_e32 v14, v54, v0
	v_sub_f32_e32 v15, v38, v0
	v_sub_f32_e32 v32, v55, v0
	v_sub_f32_e32 v33, v39, v0
	v_sub_f32_e32 v34, v56, v0
	v_sub_f32_e32 v35, v40, v0
	v_sub_f32_e32 v36, v57, v0
	v_sub_f32_e32 v37, v41, v0
	v_sub_f32_e32 v38, v58, v0
	v_sub_f32_e32 v39, v42, v0
	v_sub_f32_e32 v40, v59, v0
	v_sub_f32_e32 v41, v43, v0
	v_sub_f32_e32 v42, v60, v0
	v_sub_f32_e32 v43, v44, v0
	v_sub_f32_e32 v44, v61, v0
	v_sub_f32_e32 v45, v45, v0
	v_sub_f32_e32 v48, v62, v0
	v_sub_f32_e32 v46, v46, v0
	v_sub_f32_e32 v49, v63, v0
	v_sub_f32_e32 v0, v47, v0
	v_exp_f32_e32 v96, v2
	v_exp_f32_e32 v97, v4
	v_exp_f32_e32 v98, v6
	v_exp_f32_e32 v99, v8
	v_exp_f32_e32 v100, v10
	v_exp_f32_e32 v101, v12
	v_exp_f32_e32 v102, v14
	v_exp_f32_e32 v103, v32
	v_exp_f32_e32 v104, v34
	v_exp_f32_e32 v105, v36
	v_exp_f32_e32 v106, v38
	v_exp_f32_e32 v107, v40
	v_exp_f32_e32 v108, v42
	v_exp_f32_e32 v109, v44
	v_exp_f32_e32 v110, v48
	v_exp_f32_e32 v111, v49
	v_exp_f32_e32 v80, v3
	v_exp_f32_e32 v81, v5
	v_exp_f32_e32 v82, v7
	v_exp_f32_e32 v83, v9
	v_exp_f32_e32 v84, v11
	v_exp_f32_e32 v85, v13
	v_exp_f32_e32 v86, v15
	v_exp_f32_e32 v87, v33
	v_exp_f32_e32 v88, v35
	v_exp_f32_e32 v89, v37
	v_exp_f32_e32 v90, v39
	v_exp_f32_e32 v91, v41
	v_exp_f32_e32 v92, v43
	v_exp_f32_e32 v93, v45
	v_exp_f32_e32 v94, v46
	v_exp_f32_e32 v95, v0
	s_cbranch_vccnz .LBB0_846
	v_mov_b32_e32 v14, v1
	v_mov_b32_e32 v15, v1
	v_mov_b32_e32 v0, v1
	v_mov_b32_e32 v2, v1
	v_mov_b32_e32 v3, v1
	v_mov_b32_e32 v4, v1
	v_mov_b32_e32 v5, v1
	v_mov_b32_e32 v6, v1
	v_mov_b32_e32 v7, v1
	v_mov_b32_e32 v8, v1
	v_mov_b32_e32 v9, v1
	v_mov_b32_e32 v10, v1
	v_mov_b32_e32 v11, v1
	v_mov_b32_e32 v12, v1
	v_mov_b32_e32 v13, v1
	v_mov_b64_e32 v[62:63], v[14:15]
	v_mov_b64_e32 v[46:47], v[14:15]
	s_add_i32 s66, s1, -5
	v_lshl_add_u32 v219, v205, 2, s87
	s_mov_b32 s62, 0
	s_movk_i32 s23, 0x4000
	s_movk_i32 s10, 0x2000
	v_mov_b32_e32 v218, 0
	s_mov_b32 s67, 4
	s_mov_b64 s[6:7], s[52:53]
	s_mov_b64 s[58:59], s[50:51]
	s_mov_b64 s[60:61], s[48:49]
	v_mov_b64_e32 v[60:61], v[12:13]
	v_mov_b64_e32 v[58:59], v[10:11]
	v_mov_b64_e32 v[56:57], v[8:9]
	v_mov_b64_e32 v[54:55], v[6:7]
	v_mov_b64_e32 v[52:53], v[4:5]
	v_mov_b64_e32 v[50:51], v[2:3]
	v_mov_b64_e32 v[48:49], v[0:1]
	v_mov_b64_e32 v[44:45], v[12:13]
	v_mov_b64_e32 v[42:43], v[10:11]
	v_mov_b64_e32 v[40:41], v[8:9]
	v_mov_b64_e32 v[38:39], v[6:7]
	v_mov_b64_e32 v[36:37], v[4:5]
	v_mov_b64_e32 v[34:35], v[2:3]
	v_mov_b64_e32 v[32:33], v[0:1]
